# gate phase prologue: 4-iteration weight staging loop unrolled (16 loads issued together, then the LDS writes with counted waits); on top of P0 + attention table de-serialisation
# speedup vs baseline: 1.0059x; 1.0032x over previous
; #define LAS __attribute__((address_space(3)))
; DI void phase_gates(const Params& P, int l, int bid, int nb, LAS unsigned char* lds) {
;     ...
; #pragma unroll 4
;     for (int q = 0; q < 16; ++q) { const int e = q * 512 + threadIdx.x, n = e >> 8, c16 = e & 255;
;         *(LAS u32x4*)(lds + n * 4112 + c16 * 16) = *(const u32x4*)(Wg + (size_t)n * DM + c16 * 8); }
;     __syncthreads();
;     const LAS unsigned char* bp = lds + r * 4112 + 64 * h;
;     for (int t = bid * 8 + wid; t < MTOK / 32; t += nb * 8) {
;         const bf16_t* ap = XB + (size_t)(t * 32 + r) * DM + 32 * h;
.LBB0_186:
	v_lshl_add_u64 v[22:23], v[6:7], 0, s[0:1]
	v_add_co_u32_e32 v26, vcc, 0x1600000, v22
	v_lshl_add_u64 v[24:25], v[4:5], 0, s[0:1]
	s_nop 0
	v_addc_co_u32_e32 v27, vcc, 0, v23, vcc
	v_add_co_u32_e32 v32, vcc, 0x1604000, v22
	v_lshl_add_u64 v[30:31], v[2:3], 0, s[0:1]
	s_nop 0
	v_addc_co_u32_e32 v33, vcc, 0, v23, vcc
	global_load_dwordx4 v[206:209], v[26:27], off
	global_load_dwordx4 v[210:213], v[24:25], off
	s_nop 0
	global_load_dwordx4 v[214:217], v[32:33], off
	global_load_dwordx4 v[218:221], v[30:31], off
	s_add_u32 s0, s0, 0x8000
	s_addc_u32 s1, s1, 0
	v_lshl_add_u64 v[22:23], v[6:7], 0, s[0:1]
	v_add_co_u32_e32 v26, vcc, 0x1600000, v22
	v_lshl_add_u64 v[24:25], v[4:5], 0, s[0:1]
	s_nop 0
	v_addc_co_u32_e32 v27, vcc, 0, v23, vcc
	v_add_co_u32_e32 v32, vcc, 0x1604000, v22
	v_lshl_add_u64 v[30:31], v[2:3], 0, s[0:1]
	s_nop 0
	v_addc_co_u32_e32 v33, vcc, 0, v23, vcc
	global_load_dwordx4 v[222:225], v[26:27], off
	global_load_dwordx4 v[226:229], v[24:25], off
	s_nop 0
	global_load_dwordx4 v[230:233], v[32:33], off
	global_load_dwordx4 v[234:237], v[30:31], off
	s_add_u32 s0, s0, 0x8000
	s_addc_u32 s1, s1, 0
	v_lshl_add_u64 v[22:23], v[6:7], 0, s[0:1]
	v_add_co_u32_e32 v26, vcc, 0x1600000, v22
	v_lshl_add_u64 v[24:25], v[4:5], 0, s[0:1]
	s_nop 0
	v_addc_co_u32_e32 v27, vcc, 0, v23, vcc
	v_add_co_u32_e32 v32, vcc, 0x1604000, v22
	v_lshl_add_u64 v[30:31], v[2:3], 0, s[0:1]
	s_nop 0
	v_addc_co_u32_e32 v33, vcc, 0, v23, vcc
	global_load_dwordx4 v[164:167], v[26:27], off
	global_load_dwordx4 v[168:171], v[24:25], off
	s_nop 0
	global_load_dwordx4 v[172:175], v[32:33], off
	global_load_dwordx4 v[176:179], v[30:31], off
	s_add_u32 s0, s0, 0x8000
	s_addc_u32 s1, s1, 0
	v_lshl_add_u64 v[22:23], v[6:7], 0, s[0:1]
	v_add_co_u32_e32 v26, vcc, 0x1600000, v22
	v_lshl_add_u64 v[24:25], v[4:5], 0, s[0:1]
	s_nop 0
	v_addc_co_u32_e32 v27, vcc, 0, v23, vcc
	v_add_co_u32_e32 v32, vcc, 0x1604000, v22
	v_lshl_add_u64 v[30:31], v[2:3], 0, s[0:1]
	s_nop 0
	v_addc_co_u32_e32 v33, vcc, 0, v23, vcc
	global_load_dwordx4 v[180:183], v[26:27], off
	global_load_dwordx4 v[184:187], v[24:25], off
	s_nop 0
	global_load_dwordx4 v[188:191], v[32:33], off
	global_load_dwordx4 v[192:195], v[30:31], off
	s_add_u32 s0, s0, 0x8000
	s_addc_u32 s1, s1, 0
	v_mad_u32_u24 v13, v12, s2, v9
	v_mad_u32_u24 v30, v11, s2, v9
	v_mad_u32_u24 v31, v10, s2, v9
	v_add_u32_e32 v10, 8, v10
	v_add_u32_e32 v11, 8, v11
	v_add_u32_e32 v12, 8, v12
	s_waitcnt vmcnt(15)
	ds_write_b128 v13, v[206:209]
	s_waitcnt vmcnt(14)
	ds_write_b128 v30, v[210:213]
	s_waitcnt vmcnt(13)
	ds_write_b128 v13, v[214:217] offset:16448
	s_waitcnt vmcnt(12)
	ds_write_b128 v31, v[218:221]
	v_mad_u32_u24 v13, v12, s2, v9
	v_mad_u32_u24 v30, v11, s2, v9
	v_mad_u32_u24 v31, v10, s2, v9
	v_add_u32_e32 v10, 8, v10
	v_add_u32_e32 v11, 8, v11
	v_add_u32_e32 v12, 8, v12
	s_waitcnt vmcnt(11)
	ds_write_b128 v13, v[222:225]
	s_waitcnt vmcnt(10)
	ds_write_b128 v30, v[226:229]
	s_waitcnt vmcnt(9)
	ds_write_b128 v13, v[230:233] offset:16448
	s_waitcnt vmcnt(8)
	ds_write_b128 v31, v[234:237]
	v_mad_u32_u24 v13, v12, s2, v9
	v_mad_u32_u24 v30, v11, s2, v9
	v_mad_u32_u24 v31, v10, s2, v9
	v_add_u32_e32 v10, 8, v10
	v_add_u32_e32 v11, 8, v11
	v_add_u32_e32 v12, 8, v12
	s_waitcnt vmcnt(7)
	ds_write_b128 v13, v[164:167]
	s_waitcnt vmcnt(6)
	ds_write_b128 v30, v[168:171]
	s_waitcnt vmcnt(5)
	ds_write_b128 v13, v[172:175] offset:16448
	s_waitcnt vmcnt(4)
	ds_write_b128 v31, v[176:179]
	v_mad_u32_u24 v13, v12, s2, v9
	v_mad_u32_u24 v30, v11, s2, v9
	v_mad_u32_u24 v31, v10, s2, v9
	v_add_u32_e32 v10, 8, v10
	v_add_u32_e32 v11, 8, v11
	v_add_u32_e32 v12, 8, v12
	s_waitcnt vmcnt(3)
	ds_write_b128 v13, v[180:183]
	s_waitcnt vmcnt(2)
	ds_write_b128 v30, v[184:187]
	s_waitcnt vmcnt(1)
	ds_write_b128 v13, v[188:191] offset:16448
	s_waitcnt vmcnt(0)
	ds_write_b128 v31, v[192:195]
	v_lshrrev_b32_e32 v2, 6, v131
	v_lshl_add_u32 v95, s33, 3, v2
	s_add_u32 s4, s50, 0x1f940000
	s_movk_i32 s0, 0x500
	v_lshrrev_b32_e32 v94, 5, v131
	s_addc_u32 s5, s51, 0
	v_cmp_gt_i32_e32 vcc, s0, v95
	s_waitcnt lgkmcnt(0)
	s_barrier
	s_and_saveexec_b64 s[0:1], vcc
	s_cbranch_execz .LBB0_194
	v_and_b32_e32 v3, 1, v94
	v_lshlrev_b32_e32 v82, 6, v3
	v_mov_b32_e32 v83, 0
	v_add3_u32 v96, 0, v8, v82
	v_lshlrev_b32_e32 v97, 2, v3
	v_lshl_add_u64 v[84:85], s[4:5], 0, v[82:83]
	v_lshlrev_b32_e32 v82, 2, v1
	v_lshlrev_b32_e32 v3, 1, v131
	v_lshl_add_u64 v[4:5], s[50:51], 0, v[82:83]
	s_mov_b64 s[2:3], 0x1f440000
	v_and_b32_e32 v82, 64, v3
	v_lshlrev_b32_e32 v2, 5, v2
	v_lshl_add_u64 v[86:87], v[4:5], 0, s[2:3]
	v_lshl_add_u64 v[4:5], s[50:51], 0, v[82:83]
	s_mov_b64 s[2:3], 0x1f940100
	v_lshl_add_u32 v2, s33, 8, v2
	s_lshl_b32 s10, s94, 3
	v_lshl_add_u64 v[88:89], v[4:5], 0, s[2:3]
	v_or_b32_e32 v90, v2, v1
	s_lshl_b32 s11, s94, 8
	s_mov_b64 s[2:3], 0
	s_mov_b64 s[6:7], 0x100
	s_movk_i32 s12, 0x4ff
	s_branch .LBB0_190

; #define LAS __attribute__((address_space(3)))
; DI void phase_gates(const Params& P, int l, int bid, int nb, LAS unsigned char* lds) {
;     ...
; #pragma unroll 4
;     for (int q = 0; q < 16; ++q) { const int e = q * 512 + threadIdx.x, n = e >> 8, c16 = e & 255;
;         *(LAS u32x4*)(lds + n * 4112 + c16 * 16) = *(const u32x4*)(Wg + (size_t)n * DM + c16 * 8); }
;     __syncthreads();
;     const LAS unsigned char* bp = lds + r * 4112 + 64 * h;
;     for (int t = bid * 8 + wid; t < MTOK / 32; t += nb * 8) {
;         const bf16_t* ap = XB + (size_t)(t * 32 + r) * DM + 32 * h;
.LBB0_748:
	v_lshl_add_u64 v[20:21], v[6:7], 0, s[0:1]
	v_add_co_u32_e32 v24, vcc, 0x2c20000, v20
	v_lshl_add_u64 v[22:23], v[4:5], 0, s[0:1]
	s_nop 0
	v_addc_co_u32_e32 v25, vcc, 0, v21, vcc
	v_add_co_u32_e32 v30, vcc, 0x2c24000, v20
	v_lshl_add_u64 v[28:29], v[2:3], 0, s[0:1]
	s_nop 0
	v_addc_co_u32_e32 v31, vcc, 0, v21, vcc
	global_load_dwordx4 v[206:209], v[24:25], off
	global_load_dwordx4 v[210:213], v[22:23], off
	s_nop 0
	global_load_dwordx4 v[214:217], v[30:31], off
	global_load_dwordx4 v[218:221], v[28:29], off
	s_add_u32 s0, s0, 0x8000
	s_addc_u32 s1, s1, 0
	v_lshl_add_u64 v[20:21], v[6:7], 0, s[0:1]
	v_add_co_u32_e32 v24, vcc, 0x2c20000, v20
	v_lshl_add_u64 v[22:23], v[4:5], 0, s[0:1]
	s_nop 0
	v_addc_co_u32_e32 v25, vcc, 0, v21, vcc
	v_add_co_u32_e32 v30, vcc, 0x2c24000, v20
	v_lshl_add_u64 v[28:29], v[2:3], 0, s[0:1]
	s_nop 0
	v_addc_co_u32_e32 v31, vcc, 0, v21, vcc
	global_load_dwordx4 v[222:225], v[24:25], off
	global_load_dwordx4 v[226:229], v[22:23], off
	s_nop 0
	global_load_dwordx4 v[230:233], v[30:31], off
	global_load_dwordx4 v[234:237], v[28:29], off
	s_add_u32 s0, s0, 0x8000
	s_addc_u32 s1, s1, 0
	v_lshl_add_u64 v[20:21], v[6:7], 0, s[0:1]
	v_add_co_u32_e32 v24, vcc, 0x2c20000, v20
	v_lshl_add_u64 v[22:23], v[4:5], 0, s[0:1]
	s_nop 0
	v_addc_co_u32_e32 v25, vcc, 0, v21, vcc
	v_add_co_u32_e32 v30, vcc, 0x2c24000, v20
	v_lshl_add_u64 v[28:29], v[2:3], 0, s[0:1]
	s_nop 0
	v_addc_co_u32_e32 v31, vcc, 0, v21, vcc
	global_load_dwordx4 v[164:167], v[24:25], off
	global_load_dwordx4 v[168:171], v[22:23], off
	s_nop 0
	global_load_dwordx4 v[172:175], v[30:31], off
	global_load_dwordx4 v[176:179], v[28:29], off
	s_add_u32 s0, s0, 0x8000
	s_addc_u32 s1, s1, 0
	v_lshl_add_u64 v[20:21], v[6:7], 0, s[0:1]
	v_add_co_u32_e32 v24, vcc, 0x2c20000, v20
	v_lshl_add_u64 v[22:23], v[4:5], 0, s[0:1]
	s_nop 0
	v_addc_co_u32_e32 v25, vcc, 0, v21, vcc
	v_add_co_u32_e32 v30, vcc, 0x2c24000, v20
	v_lshl_add_u64 v[28:29], v[2:3], 0, s[0:1]
	s_nop 0
	v_addc_co_u32_e32 v31, vcc, 0, v21, vcc
	global_load_dwordx4 v[180:183], v[24:25], off
	global_load_dwordx4 v[184:187], v[22:23], off
	s_nop 0
	global_load_dwordx4 v[188:191], v[30:31], off
	global_load_dwordx4 v[192:195], v[28:29], off
	s_add_u32 s0, s0, 0x8000
	s_addc_u32 s1, s1, 0
	v_mad_u32_u24 v28, v203, s2, v9
	v_mad_u32_u24 v29, v11, s2, v9
	v_mad_u32_u24 v30, v10, s2, v9
	v_add_u32_e32 v10, 8, v10
	v_add_u32_e32 v11, 8, v11
	v_add_u32_e32 v203, 8, v203
	s_waitcnt vmcnt(15)
	ds_write_b128 v28, v[206:209]
	s_waitcnt vmcnt(14)
	ds_write_b128 v29, v[210:213]
	s_waitcnt vmcnt(13)
	ds_write_b128 v28, v[214:217] offset:16448
	s_waitcnt vmcnt(12)
	ds_write_b128 v30, v[218:221]
	v_mad_u32_u24 v28, v203, s2, v9
	v_mad_u32_u24 v29, v11, s2, v9
	v_mad_u32_u24 v30, v10, s2, v9
	v_add_u32_e32 v10, 8, v10
	v_add_u32_e32 v11, 8, v11
	v_add_u32_e32 v203, 8, v203
	s_waitcnt vmcnt(11)
	ds_write_b128 v28, v[222:225]
	s_waitcnt vmcnt(10)
	ds_write_b128 v29, v[226:229]
	s_waitcnt vmcnt(9)
	ds_write_b128 v28, v[230:233] offset:16448
	s_waitcnt vmcnt(8)
	ds_write_b128 v30, v[234:237]
	v_mad_u32_u24 v28, v203, s2, v9
	v_mad_u32_u24 v29, v11, s2, v9
	v_mad_u32_u24 v30, v10, s2, v9
	v_add_u32_e32 v10, 8, v10
	v_add_u32_e32 v11, 8, v11
	v_add_u32_e32 v203, 8, v203
	s_waitcnt vmcnt(7)
	ds_write_b128 v28, v[164:167]
	s_waitcnt vmcnt(6)
	ds_write_b128 v29, v[168:171]
	s_waitcnt vmcnt(5)
	ds_write_b128 v28, v[172:175] offset:16448
	s_waitcnt vmcnt(4)
	ds_write_b128 v30, v[176:179]
	v_mad_u32_u24 v28, v203, s2, v9
	v_mad_u32_u24 v29, v11, s2, v9
	v_mad_u32_u24 v30, v10, s2, v9
	v_add_u32_e32 v10, 8, v10
	v_add_u32_e32 v11, 8, v11
	v_add_u32_e32 v203, 8, v203
	s_waitcnt vmcnt(3)
	ds_write_b128 v28, v[180:183]
	s_waitcnt vmcnt(2)
	ds_write_b128 v29, v[184:187]
	s_waitcnt vmcnt(1)
	ds_write_b128 v28, v[188:191] offset:16448
	s_waitcnt vmcnt(0)
	ds_write_b128 v30, v[192:195]
	v_lshrrev_b32_e32 v2, 6, v131
	v_lshl_add_u32 v95, s33, 3, v2
	s_add_u32 s4, s50, 0x1f940000
	s_movk_i32 s0, 0x500
	v_lshrrev_b32_e32 v94, 5, v131
	s_addc_u32 s5, s51, 0
	v_cmp_gt_i32_e32 vcc, s0, v95
	s_waitcnt lgkmcnt(0)
	s_barrier
	s_and_saveexec_b64 s[0:1], vcc
	s_cbranch_execz .LBB0_756
	v_and_b32_e32 v3, 1, v94
	v_lshlrev_b32_e32 v82, 6, v3
	v_mov_b32_e32 v83, 0
	v_add3_u32 v96, 0, v8, v82
	v_lshlrev_b32_e32 v97, 2, v3
	v_lshl_add_u64 v[84:85], s[4:5], 0, v[82:83]
	v_lshlrev_b32_e32 v82, 2, v1
	v_lshlrev_b32_e32 v3, 1, v131
	v_lshl_add_u64 v[4:5], s[50:51], 0, v[82:83]
	s_mov_b64 s[2:3], 0x1f440000
	v_and_b32_e32 v82, 64, v3
	v_lshlrev_b32_e32 v2, 5, v2
	v_lshl_add_u64 v[86:87], v[4:5], 0, s[2:3]
	v_lshl_add_u64 v[4:5], s[50:51], 0, v[82:83]
	s_mov_b64 s[2:3], 0x1f940100
	v_lshl_add_u32 v2, s33, 8, v2
	s_lshl_b32 s10, s94, 3
	v_lshl_add_u64 v[88:89], v[4:5], 0, s[2:3]
	v_or_b32_e32 v90, v2, v1
	s_lshl_b32 s11, s94, 8
	s_mov_b64 s[2:3], 0
	s_mov_b64 s[6:7], 0x100
	s_movk_i32 s12, 0x4ff
	s_branch .LBB0_752
